# L9 branch GEMM epilogue: previous-branch merged loads hoisted into two bursts with the gate loads (was 16 serialized load+wait)
# baseline (speedup 1.0000x reference)
; DI unsigned cvtpk(float lo, float hi) { unsigned r; asm volatile("v_cvt_pk_bf16_f32 %0, %1, %2" : "=v"(r) : "v"(lo), "v"(hi)); return r; }
; DI float bf2f(bf16_t b) { return __uint_as_float(((unsigned)b) << 16); }
;   DI void operator()(const AccT& acc, const Unit& u, int wr, int wc, int fr, int fq) const {
; #pragma unroll
;     for (int ai = 0; ai < 2; ++ai)
; #pragma unroll
;       for (int m = 0; m < 4; ++m) {
;         const int row = u.pm * BM + ai * HALF + wr * 64 + m * 16 + fr;
; #pragma unroll
;         for (int bj = 0; bj < 2; ++bj) {
;           const int c8 = u.pn * BM + bj * HALF + wc * 32 + 8 * fq;
;           const bf16x8 gt = __builtin_nontemporal_load((const bf16x8*)(h + (size_t)row * NPHYS + H_GL + r * 2048 + c8));
;           bf16_t* mp = merged + (size_t)row * DM + c8;
;           f32x4 a0 = acc[ai][bj][m][0], a1 = acc[ai][bj][m][1];
; #pragma unroll
;           for (int j = 0; j < 4; ++j) { a0[j] *= bf2f((bf16_t)gt[j]); a1[j] *= bf2f((bf16_t)gt[4 + j]); }
;           if (r > 0) { const bf16x8 pv = *(const bf16x8*)mp;
; #pragma unroll
;             for (int j = 0; j < 4; ++j) { a0[j] += bf2f((bf16_t)pv[j]); a1[j] += bf2f((bf16_t)pv[4 + j]); } }
;           { u32x4 w = {cvtpk(a0[0], a0[1]), cvtpk(a0[2], a0[3]), cvtpk(a1[0], a1[1]), cvtpk(a1[2], a1[3])}; *(u32x4*)mp = w; }
;         }
;       }
;   }
.LBB0_1680:
	v_lshl_add_u32 v142, s2, 8, v148
	v_lshl_or_b32 v140, s20, 8, v150
	v_mov_b64_e32 v[144:145], s[68:69]
	v_mad_i64_i32 v[144:145], s[2:3], v142, s33, v[144:145]
	s_lshl_b32 s72, s43, 1
	v_ashrrev_i32_e32 v141, 31, v140
	v_lshl_add_u64 v[144:145], v[144:145], 0, s[72:73]
	v_lshlrev_b64 v[140:141], 1, v[140:141]
	v_lshl_add_u64 v[144:145], v[144:145], 0, v[140:141]
	v_add_co_u32_e32 v152, vcc, s82, v144
	v_ashrrev_i32_e32 v143, 31, v142
	s_nop 0
	v_addc_co_u32_e32 v153, vcc, 0, v145, vcc
	v_mov_b32_e32 v236, v152
	v_mov_b32_e32 v237, v153
	v_lshlrev_b64 v[238:239], 12, v[142:143]
	v_lshl_add_u64 v[238:239], s[70:71], 0, v[238:239]
	v_lshl_add_u64 v[238:239], v[238:239], 0, v[140:141]
	v_mov_b32_e32 v210, v236
	v_mov_b32_e32 v211, v237
	global_load_dwordx4 v[158:161], v[210:211], off nt
	global_load_dwordx4 v[162:165], v[210:211], off offset:256 nt
	s_mov_b64 s[2:3], 0x70000
	v_lshl_add_u64 v[210:211], v[210:211], 0, s[2:3]
	global_load_dwordx4 v[166:169], v[210:211], off nt
	global_load_dwordx4 v[170:173], v[210:211], off offset:256 nt
	s_mov_b64 s[2:3], 0x70000
	v_lshl_add_u64 v[210:211], v[210:211], 0, s[2:3]
	global_load_dwordx4 v[174:177], v[210:211], off nt
	global_load_dwordx4 v[178:181], v[210:211], off offset:256 nt
	s_mov_b64 s[2:3], 0x70000
	v_lshl_add_u64 v[210:211], v[210:211], 0, s[2:3]
	global_load_dwordx4 v[182:185], v[210:211], off nt
	global_load_dwordx4 v[186:189], v[210:211], off offset:256 nt
	s_cmp_eq_u64 s[4:5], 0
	s_cbranch_scc1 .Lgp_nopv0
	v_mov_b32_e32 v210, v238
	v_mov_b32_e32 v211, v239
	global_load_dwordx4 v[190:193], v[210:211], off
	global_load_dwordx4 v[194:197], v[210:211], off offset:256
	s_mov_b64 s[2:3], 0x10000
	v_lshl_add_u64 v[210:211], v[210:211], 0, s[2:3]
	global_load_dwordx4 v[198:201], v[210:211], off
	global_load_dwordx4 v[202:205], v[210:211], off offset:256
	s_mov_b64 s[2:3], 0x10000
	v_lshl_add_u64 v[210:211], v[210:211], 0, s[2:3]
	global_load_dwordx4 v[206:209], v[210:211], off
	global_load_dwordx4 v[214:217], v[210:211], off offset:256
	s_mov_b64 s[2:3], 0x10000
	v_lshl_add_u64 v[210:211], v[210:211], 0, s[2:3]
	global_load_dwordx4 v[224:227], v[210:211], off
	global_load_dwordx4 v[232:235], v[210:211], off offset:256
.Lgp_nopv0:
	s_waitcnt vmcnt(0)
	v_mov_b32_e32 v152, v158
	v_mov_b32_e32 v153, v159
	v_mov_b32_e32 v154, v160
	v_mov_b32_e32 v155, v161
	v_lshlrev_b64 v[146:147], 12, v[142:143]
	v_lshl_add_u64 v[156:157], s[70:71], 0, v[146:147]
	v_cndmask_b32_e64 v143, 0, 1, s[4:5]
	v_cmp_ne_u32_e64 s[2:3], 1, v143
	s_andn2_b64 vcc, exec, s[4:5]
	v_and_b32_e32 v147, 0xffff0000, v152
	v_lshlrev_b32_e32 v146, 16, v152
	v_pk_mul_f32 v[126:127], v[126:127], v[146:147]
	v_and_b32_e32 v147, 0xffff0000, v154
	v_lshlrev_b32_e32 v146, 16, v154
	v_pk_mul_f32 v[146:147], v[122:123], v[146:147]
	v_and_b32_e32 v123, 0xffff0000, v153
	v_lshlrev_b32_e32 v122, 16, v153
	v_pk_mul_f32 v[128:129], v[128:129], v[122:123]
	v_and_b32_e32 v123, 0xffff0000, v155
	v_lshlrev_b32_e32 v122, 16, v155
	v_pk_mul_f32 v[124:125], v[124:125], v[122:123]
	v_lshl_add_u64 v[122:123], v[156:157], 0, v[140:141]
	s_cbranch_vccnz .LBB0_1682
	v_mov_b32_e32 v152, v190
	v_mov_b32_e32 v153, v191
	v_mov_b32_e32 v154, v192
	v_mov_b32_e32 v155, v193
	v_and_b32_e32 v157, 0xffff0000, v152
	v_lshlrev_b32_e32 v156, 16, v152
	v_pk_add_f32 v[126:127], v[126:127], v[156:157]
	v_and_b32_e32 v157, 0xffff0000, v154
	v_lshlrev_b32_e32 v156, 16, v154
	v_pk_add_f32 v[146:147], v[146:147], v[156:157]
	v_and_b32_e32 v157, 0xffff0000, v153
	v_lshlrev_b32_e32 v156, 16, v153
	v_and_b32_e32 v153, 0xffff0000, v155
	v_lshlrev_b32_e32 v152, 16, v155
	v_pk_add_f32 v[128:129], v[128:129], v[156:157]
	v_pk_add_f32 v[124:125], v[124:125], v[152:153]
.LBB0_1682:
	v_lshl_add_u64 v[144:145], v[144:145], 0, s[76:77]
	v_cvt_pk_bf16_f32 v126, v126, v127
	v_cvt_pk_bf16_f32 v127, v128, v129
	v_cvt_pk_bf16_f32 v128, v146, v147
	v_cvt_pk_bf16_f32 v129, v124, v125
	v_mov_b32_e32 v144, v162
	v_mov_b32_e32 v145, v163
	v_mov_b32_e32 v146, v164
	v_mov_b32_e32 v147, v165
	s_and_b64 vcc, exec, s[2:3]
	global_store_dwordx4 v[122:123], v[126:129], off
	v_mov_b32_e32 v212, v218
	v_and_b32_e32 v125, 0xffff0000, v144
	v_lshlrev_b32_e32 v124, 16, v144
	v_and_b32_e32 v127, 0xffff0000, v146
	v_lshlrev_b32_e32 v126, 16, v146
	v_and_b32_e32 v129, 0xffff0000, v145
	v_lshlrev_b32_e32 v128, 16, v145
	v_and_b32_e32 v145, 0xffff0000, v147
	v_lshlrev_b32_e32 v144, 16, v147
	v_pk_mul_f32 v[118:119], v[118:119], v[124:125]
	v_pk_mul_f32 v[114:115], v[114:115], v[126:127]
	v_pk_mul_f32 v[120:121], v[120:121], v[128:129]
	v_pk_mul_f32 v[116:117], v[116:117], v[144:145]
	s_cbranch_vccnz .LBB0_1684
	v_mov_b32_e32 v124, v194
	v_mov_b32_e32 v125, v195
	v_mov_b32_e32 v126, v196
	v_mov_b32_e32 v127, v197
	v_and_b32_e32 v129, 0xffff0000, v124
	v_lshlrev_b32_e32 v128, 16, v124
	v_pk_add_f32 v[118:119], v[118:119], v[128:129]
	v_and_b32_e32 v129, 0xffff0000, v126
	v_lshlrev_b32_e32 v128, 16, v126
	v_pk_add_f32 v[114:115], v[114:115], v[128:129]
	v_and_b32_e32 v129, 0xffff0000, v125
	v_lshlrev_b32_e32 v128, 16, v125
	v_and_b32_e32 v125, 0xffff0000, v127
	v_lshlrev_b32_e32 v124, 16, v127
	v_pk_add_f32 v[120:121], v[120:121], v[128:129]
	v_pk_add_f32 v[116:117], v[116:117], v[124:125]
; DI unsigned cvtpk(float lo, float hi) { unsigned r; asm volatile("v_cvt_pk_bf16_f32 %0, %1, %2" : "=v"(r) : "v"(lo), "v"(hi)); return r; }
; DI float bf2f(bf16_t b) { return __uint_as_float(((unsigned)b) << 16); }
;   DI void operator()(const AccT& acc, const Unit& u, int wr, int wc, int fr, int fq) const {
; #pragma unroll
;     for (int ai = 0; ai < 2; ++ai)
; #pragma unroll
;       for (int m = 0; m < 4; ++m) {
;         const int row = u.pm * BM + ai * HALF + wr * 64 + m * 16 + fr;
; #pragma unroll
;         for (int bj = 0; bj < 2; ++bj) {
;           const int c8 = u.pn * BM + bj * HALF + wc * 32 + 8 * fq;
;           const bf16x8 gt = __builtin_nontemporal_load((const bf16x8*)(h + (size_t)row * NPHYS + H_GL + r * 2048 + c8));
;           bf16_t* mp = merged + (size_t)row * DM + c8;
;           f32x4 a0 = acc[ai][bj][m][0], a1 = acc[ai][bj][m][1];
; #pragma unroll
;           for (int j = 0; j < 4; ++j) { a0[j] *= bf2f((bf16_t)gt[j]); a1[j] *= bf2f((bf16_t)gt[4 + j]); }
;           if (r > 0) { const bf16x8 pv = *(const bf16x8*)mp;
; #pragma unroll
;             for (int j = 0; j < 4; ++j) { a0[j] += bf2f((bf16_t)pv[j]); a1[j] += bf2f((bf16_t)pv[4 + j]); } }
;           { u32x4 w = {cvtpk(a0[0], a0[1]), cvtpk(a0[2], a0[3]), cvtpk(a1[0], a1[1]), cvtpk(a1[2], a1[3])}; *(u32x4*)mp = w; }
;         }
;       }
;   }
.LBB0_1684:
	v_cvt_pk_bf16_f32 v118, v118, v119
	v_cvt_pk_bf16_f32 v119, v120, v121
	v_cvt_pk_bf16_f32 v120, v114, v115
	v_or_b32_e32 v114, 16, v142
	v_cvt_pk_bf16_f32 v121, v116, v117
	global_store_dwordx4 v[122:123], v[118:121], off offset:256
	v_ashrrev_i32_e32 v115, 31, v114
	v_lshlrev_b64 v[116:117], 12, v[114:115]
	v_mov_b64_e32 v[118:119], s[68:69]
	v_mad_i64_i32 v[114:115], s[22:23], v114, s33, v[118:119]
	v_lshl_add_u64 v[114:115], v[114:115], 0, s[72:73]
	v_lshl_add_u64 v[114:115], v[114:115], 0, v[140:141]
	v_add_co_u32_e32 v118, vcc, s82, v114
	v_lshl_add_u64 v[122:123], s[70:71], 0, v[116:117]
	s_nop 0
	v_addc_co_u32_e32 v119, vcc, 0, v115, vcc
	v_mov_b32_e32 v118, v166
	v_mov_b32_e32 v119, v167
	v_mov_b32_e32 v120, v168
	v_mov_b32_e32 v121, v169
	s_and_b64 vcc, exec, s[2:3]
	v_and_b32_e32 v117, 0xffff0000, v118
	v_lshlrev_b32_e32 v116, 16, v118
	v_pk_mul_f32 v[110:111], v[110:111], v[116:117]
	v_and_b32_e32 v117, 0xffff0000, v120
	v_lshlrev_b32_e32 v116, 16, v120
	v_pk_mul_f32 v[116:117], v[106:107], v[116:117]
	v_and_b32_e32 v107, 0xffff0000, v119
	v_lshlrev_b32_e32 v106, 16, v119
	v_pk_mul_f32 v[112:113], v[112:113], v[106:107]
	v_and_b32_e32 v107, 0xffff0000, v121
	v_lshlrev_b32_e32 v106, 16, v121
	v_pk_mul_f32 v[108:109], v[108:109], v[106:107]
	v_lshl_add_u64 v[106:107], v[122:123], 0, v[140:141]
	s_cbranch_vccnz .LBB0_1686
	v_mov_b32_e32 v118, v198
	v_mov_b32_e32 v119, v199
	v_mov_b32_e32 v120, v200
	v_mov_b32_e32 v121, v201
	v_and_b32_e32 v123, 0xffff0000, v118
	v_lshlrev_b32_e32 v122, 16, v118
	v_pk_add_f32 v[110:111], v[110:111], v[122:123]
	v_and_b32_e32 v123, 0xffff0000, v120
	v_lshlrev_b32_e32 v122, 16, v120
	v_pk_add_f32 v[116:117], v[116:117], v[122:123]
	v_and_b32_e32 v123, 0xffff0000, v119
	v_lshlrev_b32_e32 v122, 16, v119
	v_and_b32_e32 v119, 0xffff0000, v121
	v_lshlrev_b32_e32 v118, 16, v121
	v_pk_add_f32 v[112:113], v[112:113], v[122:123]
	v_pk_add_f32 v[108:109], v[108:109], v[118:119]
.LBB0_1686:
	v_lshl_add_u64 v[114:115], v[114:115], 0, s[76:77]
	v_cvt_pk_bf16_f32 v110, v110, v111
	v_cvt_pk_bf16_f32 v111, v112, v113
	v_cvt_pk_bf16_f32 v112, v116, v117
	v_cvt_pk_bf16_f32 v113, v108, v109
	v_mov_b32_e32 v114, v170
	v_mov_b32_e32 v115, v171
	v_mov_b32_e32 v116, v172
	v_mov_b32_e32 v117, v173
	s_and_b64 vcc, exec, s[2:3]
	global_store_dwordx4 v[106:107], v[110:113], off
	v_and_b32_e32 v109, 0xffff0000, v114
	v_lshlrev_b32_e32 v108, 16, v114
	v_and_b32_e32 v111, 0xffff0000, v116
	v_lshlrev_b32_e32 v110, 16, v116
	v_and_b32_e32 v113, 0xffff0000, v115
	v_lshlrev_b32_e32 v112, 16, v115
	v_and_b32_e32 v115, 0xffff0000, v117
	v_lshlrev_b32_e32 v114, 16, v117
	v_pk_mul_f32 v[102:103], v[102:103], v[108:109]
	v_pk_mul_f32 v[98:99], v[98:99], v[110:111]
	v_pk_mul_f32 v[104:105], v[104:105], v[112:113]
	v_pk_mul_f32 v[100:101], v[100:101], v[114:115]
	s_cbranch_vccnz .LBB0_1688
	v_mov_b32_e32 v108, v202
	v_mov_b32_e32 v109, v203
	v_mov_b32_e32 v110, v204
	v_mov_b32_e32 v111, v205
	v_and_b32_e32 v113, 0xffff0000, v108
	v_lshlrev_b32_e32 v112, 16, v108
	v_pk_add_f32 v[102:103], v[102:103], v[112:113]
	v_and_b32_e32 v113, 0xffff0000, v110
	v_lshlrev_b32_e32 v112, 16, v110
	v_pk_add_f32 v[98:99], v[98:99], v[112:113]
	v_and_b32_e32 v113, 0xffff0000, v109
	v_lshlrev_b32_e32 v112, 16, v109
	v_and_b32_e32 v109, 0xffff0000, v111
	v_lshlrev_b32_e32 v108, 16, v111
	v_pk_add_f32 v[104:105], v[104:105], v[112:113]
	v_pk_add_f32 v[100:101], v[100:101], v[108:109]
.LBB0_1688:
	v_cvt_pk_bf16_f32 v102, v102, v103
	v_cvt_pk_bf16_f32 v103, v104, v105
	v_cvt_pk_bf16_f32 v104, v98, v99
	v_or_b32_e32 v98, 32, v142
	v_cvt_pk_bf16_f32 v105, v100, v101
	global_store_dwordx4 v[106:107], v[102:105], off offset:256
	v_ashrrev_i32_e32 v99, 31, v98
	v_lshlrev_b64 v[100:101], 12, v[98:99]
	v_mov_b64_e32 v[102:103], s[68:69]
	v_mad_i64_i32 v[98:99], s[22:23], v98, s33, v[102:103]
	v_lshl_add_u64 v[98:99], v[98:99], 0, s[72:73]
	v_lshl_add_u64 v[98:99], v[98:99], 0, v[140:141]
	v_add_co_u32_e32 v102, vcc, s82, v98
	v_lshl_add_u64 v[106:107], s[70:71], 0, v[100:101]
	s_nop 0
	v_addc_co_u32_e32 v103, vcc, 0, v99, vcc
	v_mov_b32_e32 v102, v174
	v_mov_b32_e32 v103, v175
	v_mov_b32_e32 v104, v176
	v_mov_b32_e32 v105, v177
	s_and_b64 vcc, exec, s[2:3]
	v_and_b32_e32 v101, 0xffff0000, v102
	v_lshlrev_b32_e32 v100, 16, v102
	v_pk_mul_f32 v[94:95], v[94:95], v[100:101]
	v_and_b32_e32 v101, 0xffff0000, v104
	v_lshlrev_b32_e32 v100, 16, v104
	v_pk_mul_f32 v[100:101], v[90:91], v[100:101]
	v_and_b32_e32 v91, 0xffff0000, v103
	v_lshlrev_b32_e32 v90, 16, v103
	v_pk_mul_f32 v[96:97], v[96:97], v[90:91]
	v_and_b32_e32 v91, 0xffff0000, v105
	v_lshlrev_b32_e32 v90, 16, v105
	v_pk_mul_f32 v[92:93], v[92:93], v[90:91]
	v_lshl_add_u64 v[90:91], v[106:107], 0, v[140:141]
	s_cbranch_vccnz .LBB0_1690
	v_mov_b32_e32 v102, v206
	v_mov_b32_e32 v103, v207
	v_mov_b32_e32 v104, v208
	v_mov_b32_e32 v105, v209
	v_and_b32_e32 v107, 0xffff0000, v102
	v_lshlrev_b32_e32 v106, 16, v102
	v_pk_add_f32 v[94:95], v[94:95], v[106:107]
	v_and_b32_e32 v107, 0xffff0000, v104
	v_lshlrev_b32_e32 v106, 16, v104
	v_pk_add_f32 v[100:101], v[100:101], v[106:107]
	v_and_b32_e32 v107, 0xffff0000, v103
	v_lshlrev_b32_e32 v106, 16, v103
	v_and_b32_e32 v103, 0xffff0000, v105
	v_lshlrev_b32_e32 v102, 16, v105
	v_pk_add_f32 v[96:97], v[96:97], v[106:107]
	v_pk_add_f32 v[92:93], v[92:93], v[102:103]
; DI unsigned cvtpk(float lo, float hi) { unsigned r; asm volatile("v_cvt_pk_bf16_f32 %0, %1, %2" : "=v"(r) : "v"(lo), "v"(hi)); return r; }
; DI float bf2f(bf16_t b) { return __uint_as_float(((unsigned)b) << 16); }
;   DI void operator()(const AccT& acc, const Unit& u, int wr, int wc, int fr, int fq) const {
; #pragma unroll
;     for (int ai = 0; ai < 2; ++ai)
; #pragma unroll
;       for (int m = 0; m < 4; ++m) {
;         const int row = u.pm * BM + ai * HALF + wr * 64 + m * 16 + fr;
; #pragma unroll
;         for (int bj = 0; bj < 2; ++bj) {
;           const int c8 = u.pn * BM + bj * HALF + wc * 32 + 8 * fq;
;           const bf16x8 gt = __builtin_nontemporal_load((const bf16x8*)(h + (size_t)row * NPHYS + H_GL + r * 2048 + c8));
;           bf16_t* mp = merged + (size_t)row * DM + c8;
;           f32x4 a0 = acc[ai][bj][m][0], a1 = acc[ai][bj][m][1];
; #pragma unroll
;           for (int j = 0; j < 4; ++j) { a0[j] *= bf2f((bf16_t)gt[j]); a1[j] *= bf2f((bf16_t)gt[4 + j]); }
;           if (r > 0) { const bf16x8 pv = *(const bf16x8*)mp;
; #pragma unroll
;             for (int j = 0; j < 4; ++j) { a0[j] += bf2f((bf16_t)pv[j]); a1[j] += bf2f((bf16_t)pv[4 + j]); } }
;           { u32x4 w = {cvtpk(a0[0], a0[1]), cvtpk(a0[2], a0[3]), cvtpk(a1[0], a1[1]), cvtpk(a1[2], a1[3])}; *(u32x4*)mp = w; }
;         }
;       }
;   }
.LBB0_1690:
	v_lshl_add_u64 v[98:99], v[98:99], 0, s[76:77]
	v_cvt_pk_bf16_f32 v94, v94, v95
	v_cvt_pk_bf16_f32 v95, v96, v97
	v_cvt_pk_bf16_f32 v96, v100, v101
	v_cvt_pk_bf16_f32 v97, v92, v93
	v_mov_b32_e32 v98, v178
	v_mov_b32_e32 v99, v179
	v_mov_b32_e32 v100, v180
	v_mov_b32_e32 v101, v181
	s_and_b64 vcc, exec, s[2:3]
	global_store_dwordx4 v[90:91], v[94:97], off
	v_and_b32_e32 v93, 0xffff0000, v98
	v_lshlrev_b32_e32 v92, 16, v98
	v_and_b32_e32 v95, 0xffff0000, v100
	v_lshlrev_b32_e32 v94, 16, v100
	v_and_b32_e32 v97, 0xffff0000, v99
	v_lshlrev_b32_e32 v96, 16, v99
	v_and_b32_e32 v99, 0xffff0000, v101
	v_lshlrev_b32_e32 v98, 16, v101
	v_pk_mul_f32 v[86:87], v[86:87], v[92:93]
	v_pk_mul_f32 v[82:83], v[82:83], v[94:95]
	v_pk_mul_f32 v[88:89], v[88:89], v[96:97]
	v_pk_mul_f32 v[84:85], v[84:85], v[98:99]
	s_cbranch_vccnz .LBB0_1692
	v_mov_b32_e32 v92, v214
	v_mov_b32_e32 v93, v215
	v_mov_b32_e32 v94, v216
	v_mov_b32_e32 v95, v217
	v_and_b32_e32 v97, 0xffff0000, v92
	v_lshlrev_b32_e32 v96, 16, v92
	v_pk_add_f32 v[86:87], v[86:87], v[96:97]
	v_and_b32_e32 v97, 0xffff0000, v94
	v_lshlrev_b32_e32 v96, 16, v94
	v_pk_add_f32 v[82:83], v[82:83], v[96:97]
	v_and_b32_e32 v97, 0xffff0000, v93
	v_lshlrev_b32_e32 v96, 16, v93
	v_and_b32_e32 v93, 0xffff0000, v95
	v_lshlrev_b32_e32 v92, 16, v95
	v_pk_add_f32 v[88:89], v[88:89], v[96:97]
	v_pk_add_f32 v[84:85], v[84:85], v[92:93]
.LBB0_1692:
	v_cvt_pk_bf16_f32 v86, v86, v87
	v_cvt_pk_bf16_f32 v87, v88, v89
	v_cvt_pk_bf16_f32 v88, v82, v83
	v_or_b32_e32 v82, 48, v142
	v_cvt_pk_bf16_f32 v89, v84, v85
	global_store_dwordx4 v[90:91], v[86:89], off offset:256
	v_ashrrev_i32_e32 v83, 31, v82
	v_lshlrev_b64 v[84:85], 12, v[82:83]
	v_mov_b64_e32 v[86:87], s[68:69]
	v_mad_i64_i32 v[82:83], s[22:23], v82, s33, v[86:87]
	v_lshl_add_u64 v[82:83], v[82:83], 0, s[72:73]
	v_lshl_add_u64 v[82:83], v[82:83], 0, v[140:141]
	v_add_co_u32_e32 v86, vcc, s82, v82
	v_lshl_add_u64 v[90:91], s[70:71], 0, v[84:85]
	s_nop 0
	v_addc_co_u32_e32 v87, vcc, 0, v83, vcc
	v_mov_b32_e32 v86, v182
	v_mov_b32_e32 v87, v183
	v_mov_b32_e32 v88, v184
	v_mov_b32_e32 v89, v185
	s_and_b64 vcc, exec, s[2:3]
	v_and_b32_e32 v85, 0xffff0000, v86
	v_lshlrev_b32_e32 v84, 16, v86
	v_pk_mul_f32 v[78:79], v[78:79], v[84:85]
	v_and_b32_e32 v85, 0xffff0000, v88
	v_lshlrev_b32_e32 v84, 16, v88
	v_pk_mul_f32 v[84:85], v[74:75], v[84:85]
	v_and_b32_e32 v75, 0xffff0000, v87
	v_lshlrev_b32_e32 v74, 16, v87
	v_pk_mul_f32 v[80:81], v[80:81], v[74:75]
	v_and_b32_e32 v75, 0xffff0000, v89
	v_lshlrev_b32_e32 v74, 16, v89
	v_pk_mul_f32 v[76:77], v[76:77], v[74:75]
	v_lshl_add_u64 v[74:75], v[90:91], 0, v[140:141]
	s_cbranch_vccnz .LBB0_1694
	v_mov_b32_e32 v86, v224
	v_mov_b32_e32 v87, v225
	v_mov_b32_e32 v88, v226
	v_mov_b32_e32 v89, v227
	v_and_b32_e32 v91, 0xffff0000, v86
	v_lshlrev_b32_e32 v90, 16, v86
	v_pk_add_f32 v[78:79], v[78:79], v[90:91]
	v_and_b32_e32 v91, 0xffff0000, v88
	v_lshlrev_b32_e32 v90, 16, v88
	v_pk_add_f32 v[84:85], v[84:85], v[90:91]
	v_and_b32_e32 v91, 0xffff0000, v87
	v_lshlrev_b32_e32 v90, 16, v87
	v_and_b32_e32 v87, 0xffff0000, v89
	v_lshlrev_b32_e32 v86, 16, v89
	v_pk_add_f32 v[80:81], v[80:81], v[90:91]
	v_pk_add_f32 v[76:77], v[76:77], v[86:87]
.LBB0_1694:
	v_lshl_add_u64 v[82:83], v[82:83], 0, s[76:77]
	v_cvt_pk_bf16_f32 v78, v78, v79
	v_cvt_pk_bf16_f32 v79, v80, v81
	v_cvt_pk_bf16_f32 v80, v84, v85
	v_cvt_pk_bf16_f32 v81, v76, v77
	v_mov_b32_e32 v82, v186
	v_mov_b32_e32 v83, v187
	v_mov_b32_e32 v84, v188
	v_mov_b32_e32 v85, v189
	s_and_b64 vcc, exec, s[2:3]
	global_store_dwordx4 v[74:75], v[78:81], off
	v_and_b32_e32 v77, 0xffff0000, v82
	v_lshlrev_b32_e32 v76, 16, v82
	v_and_b32_e32 v79, 0xffff0000, v84
	v_lshlrev_b32_e32 v78, 16, v84
	v_and_b32_e32 v81, 0xffff0000, v83
	v_lshlrev_b32_e32 v80, 16, v83
	v_and_b32_e32 v83, 0xffff0000, v85
	v_lshlrev_b32_e32 v82, 16, v85
	v_pk_mul_f32 v[70:71], v[70:71], v[76:77]
	v_pk_mul_f32 v[66:67], v[66:67], v[78:79]
	v_pk_mul_f32 v[72:73], v[72:73], v[80:81]
	v_pk_mul_f32 v[68:69], v[68:69], v[82:83]
	s_cbranch_vccnz .LBB0_1696
	v_mov_b32_e32 v76, v232
	v_mov_b32_e32 v77, v233
	v_mov_b32_e32 v78, v234
	v_mov_b32_e32 v79, v235
	v_and_b32_e32 v81, 0xffff0000, v76
	v_lshlrev_b32_e32 v80, 16, v76
	v_pk_add_f32 v[70:71], v[70:71], v[80:81]
	v_and_b32_e32 v81, 0xffff0000, v78
	v_lshlrev_b32_e32 v80, 16, v78
	v_pk_add_f32 v[66:67], v[66:67], v[80:81]
	v_and_b32_e32 v81, 0xffff0000, v77
	v_lshlrev_b32_e32 v80, 16, v77
	v_and_b32_e32 v77, 0xffff0000, v79
	v_lshlrev_b32_e32 v76, 16, v79
	v_pk_add_f32 v[72:73], v[72:73], v[80:81]
	v_pk_add_f32 v[68:69], v[68:69], v[76:77]
; DI unsigned cvtpk(float lo, float hi) { unsigned r; asm volatile("v_cvt_pk_bf16_f32 %0, %1, %2" : "=v"(r) : "v"(lo), "v"(hi)); return r; }
; DI float bf2f(bf16_t b) { return __uint_as_float(((unsigned)b) << 16); }
;   DI void operator()(const AccT& acc, const Unit& u, int wr, int wc, int fr, int fq) const {
; #pragma unroll
;     for (int ai = 0; ai < 2; ++ai)
; #pragma unroll
;       for (int m = 0; m < 4; ++m) {
;         const int row = u.pm * BM + ai * HALF + wr * 64 + m * 16 + fr;
; #pragma unroll
;         for (int bj = 0; bj < 2; ++bj) {
;           const int c8 = u.pn * BM + bj * HALF + wc * 32 + 8 * fq;
;           const bf16x8 gt = __builtin_nontemporal_load((const bf16x8*)(h + (size_t)row * NPHYS + H_GL + r * 2048 + c8));
;           bf16_t* mp = merged + (size_t)row * DM + c8;
;           f32x4 a0 = acc[ai][bj][m][0], a1 = acc[ai][bj][m][1];
; #pragma unroll
;           for (int j = 0; j < 4; ++j) { a0[j] *= bf2f((bf16_t)gt[j]); a1[j] *= bf2f((bf16_t)gt[4 + j]); }
;           if (r > 0) { const bf16x8 pv = *(const bf16x8*)mp;
; #pragma unroll
;             for (int j = 0; j < 4; ++j) { a0[j] += bf2f((bf16_t)pv[j]); a1[j] += bf2f((bf16_t)pv[4 + j]); } }
;           { u32x4 w = {cvtpk(a0[0], a0[1]), cvtpk(a0[2], a0[3]), cvtpk(a1[0], a1[1]), cvtpk(a1[2], a1[3])}; *(u32x4*)mp = w; }
;         }
;       }
;   }
.LBB0_1696:
	v_cvt_pk_bf16_f32 v70, v70, v71
	v_cvt_pk_bf16_f32 v71, v72, v73
	v_cvt_pk_bf16_f32 v72, v66, v67
	v_add_u32_e32 v66, 0x80, v142
	v_cvt_pk_bf16_f32 v73, v68, v69
	global_store_dwordx4 v[74:75], v[70:73], off offset:256
	v_ashrrev_i32_e32 v67, 31, v66
	v_lshlrev_b64 v[68:69], 12, v[66:67]
	v_mov_b64_e32 v[70:71], s[68:69]
	v_mad_i64_i32 v[66:67], s[22:23], v66, s33, v[70:71]
	v_lshl_add_u64 v[66:67], v[66:67], 0, s[72:73]
	v_lshl_add_u64 v[66:67], v[66:67], 0, v[140:141]
	v_add_co_u32_e32 v70, vcc, s82, v66
	v_lshl_add_u64 v[74:75], s[70:71], 0, v[68:69]
	s_nop 0
	v_addc_co_u32_e32 v71, vcc, 0, v67, vcc
	s_mov_b64 s[22:23], 0x380000
	v_lshl_add_u64 v[236:237], v[236:237], 0, s[22:23]
	s_mov_b64 s[22:23], 0x80000
	v_lshl_add_u64 v[238:239], v[238:239], 0, s[22:23]
	v_mov_b32_e32 v210, v236
	v_mov_b32_e32 v211, v237
	global_load_dwordx4 v[158:161], v[210:211], off nt
	global_load_dwordx4 v[162:165], v[210:211], off offset:256 nt
	s_mov_b64 s[22:23], 0x70000
	v_lshl_add_u64 v[210:211], v[210:211], 0, s[22:23]
	global_load_dwordx4 v[166:169], v[210:211], off nt
	global_load_dwordx4 v[170:173], v[210:211], off offset:256 nt
	s_mov_b64 s[22:23], 0x70000
	v_lshl_add_u64 v[210:211], v[210:211], 0, s[22:23]
	global_load_dwordx4 v[174:177], v[210:211], off nt
	global_load_dwordx4 v[178:181], v[210:211], off offset:256 nt
	s_mov_b64 s[22:23], 0x70000
	v_lshl_add_u64 v[210:211], v[210:211], 0, s[22:23]
	global_load_dwordx4 v[182:185], v[210:211], off nt
	global_load_dwordx4 v[186:189], v[210:211], off offset:256 nt
	s_cmp_eq_u64 s[4:5], 0
	s_cbranch_scc1 .Lgp_nopv1
	v_mov_b32_e32 v210, v238
	v_mov_b32_e32 v211, v239
	global_load_dwordx4 v[190:193], v[210:211], off
	global_load_dwordx4 v[194:197], v[210:211], off offset:256
	s_mov_b64 s[22:23], 0x10000
	v_lshl_add_u64 v[210:211], v[210:211], 0, s[22:23]
	global_load_dwordx4 v[198:201], v[210:211], off
	global_load_dwordx4 v[202:205], v[210:211], off offset:256
	s_mov_b64 s[22:23], 0x10000
	v_lshl_add_u64 v[210:211], v[210:211], 0, s[22:23]
	global_load_dwordx4 v[206:209], v[210:211], off
	global_load_dwordx4 v[214:217], v[210:211], off offset:256
	s_mov_b64 s[22:23], 0x10000
	v_lshl_add_u64 v[210:211], v[210:211], 0, s[22:23]
	global_load_dwordx4 v[224:227], v[210:211], off
	global_load_dwordx4 v[232:235], v[210:211], off offset:256
.Lgp_nopv1:
	s_waitcnt vmcnt(0)
	v_mov_b32_e32 v70, v158
	v_mov_b32_e32 v71, v159
	v_mov_b32_e32 v72, v160
	v_mov_b32_e32 v73, v161
	s_and_b64 vcc, exec, s[2:3]
	v_and_b32_e32 v69, 0xffff0000, v70
	v_lshlrev_b32_e32 v68, 16, v70
	v_pk_mul_f32 v[62:63], v[62:63], v[68:69]
	v_and_b32_e32 v69, 0xffff0000, v72
	v_lshlrev_b32_e32 v68, 16, v72
	v_pk_mul_f32 v[68:69], v[58:59], v[68:69]
	v_and_b32_e32 v59, 0xffff0000, v71
	v_lshlrev_b32_e32 v58, 16, v71
	v_pk_mul_f32 v[64:65], v[64:65], v[58:59]
	v_and_b32_e32 v59, 0xffff0000, v73
	v_lshlrev_b32_e32 v58, 16, v73
	v_pk_mul_f32 v[60:61], v[60:61], v[58:59]
	v_lshl_add_u64 v[58:59], v[74:75], 0, v[140:141]
	s_cbranch_vccnz .LBB0_1698
	v_mov_b32_e32 v70, v190
	v_mov_b32_e32 v71, v191
	v_mov_b32_e32 v72, v192
	v_mov_b32_e32 v73, v193
	v_and_b32_e32 v75, 0xffff0000, v70
	v_lshlrev_b32_e32 v74, 16, v70
	v_pk_add_f32 v[62:63], v[62:63], v[74:75]
	v_and_b32_e32 v75, 0xffff0000, v72
	v_lshlrev_b32_e32 v74, 16, v72
	v_pk_add_f32 v[68:69], v[68:69], v[74:75]
	v_and_b32_e32 v75, 0xffff0000, v71
	v_lshlrev_b32_e32 v74, 16, v71
	v_and_b32_e32 v71, 0xffff0000, v73
	v_lshlrev_b32_e32 v70, 16, v73
	v_pk_add_f32 v[64:65], v[64:65], v[74:75]
	v_pk_add_f32 v[60:61], v[60:61], v[70:71]
.LBB0_1698:
	v_lshl_add_u64 v[66:67], v[66:67], 0, s[76:77]
	v_cvt_pk_bf16_f32 v62, v62, v63
	v_cvt_pk_bf16_f32 v63, v64, v65
	v_cvt_pk_bf16_f32 v64, v68, v69
	v_cvt_pk_bf16_f32 v65, v60, v61
	v_mov_b32_e32 v66, v162
	v_mov_b32_e32 v67, v163
	v_mov_b32_e32 v68, v164
	v_mov_b32_e32 v69, v165
	s_and_b64 vcc, exec, s[2:3]
	global_store_dwordx4 v[58:59], v[62:65], off
	v_and_b32_e32 v61, 0xffff0000, v66
	v_lshlrev_b32_e32 v60, 16, v66
	v_and_b32_e32 v63, 0xffff0000, v68
	v_lshlrev_b32_e32 v62, 16, v68
	v_and_b32_e32 v65, 0xffff0000, v67
	v_lshlrev_b32_e32 v64, 16, v67
	v_and_b32_e32 v67, 0xffff0000, v69
	v_lshlrev_b32_e32 v66, 16, v69
	v_pk_mul_f32 v[54:55], v[54:55], v[60:61]
	v_pk_mul_f32 v[50:51], v[50:51], v[62:63]
	v_pk_mul_f32 v[56:57], v[56:57], v[64:65]
	v_pk_mul_f32 v[52:53], v[52:53], v[66:67]
	s_cbranch_vccnz .LBB0_1700
	v_mov_b32_e32 v60, v194
	v_mov_b32_e32 v61, v195
	v_mov_b32_e32 v62, v196
	v_mov_b32_e32 v63, v197
	v_and_b32_e32 v65, 0xffff0000, v60
	v_lshlrev_b32_e32 v64, 16, v60
	v_pk_add_f32 v[54:55], v[54:55], v[64:65]
	v_and_b32_e32 v65, 0xffff0000, v62
	v_lshlrev_b32_e32 v64, 16, v62
	v_pk_add_f32 v[50:51], v[50:51], v[64:65]
	v_and_b32_e32 v65, 0xffff0000, v61
	v_lshlrev_b32_e32 v64, 16, v61
	v_and_b32_e32 v61, 0xffff0000, v63
	v_lshlrev_b32_e32 v60, 16, v63
	v_pk_add_f32 v[56:57], v[56:57], v[64:65]
	v_pk_add_f32 v[52:53], v[52:53], v[60:61]
; DI unsigned cvtpk(float lo, float hi) { unsigned r; asm volatile("v_cvt_pk_bf16_f32 %0, %1, %2" : "=v"(r) : "v"(lo), "v"(hi)); return r; }
; DI float bf2f(bf16_t b) { return __uint_as_float(((unsigned)b) << 16); }
;   DI void operator()(const AccT& acc, const Unit& u, int wr, int wc, int fr, int fq) const {
; #pragma unroll
;     for (int ai = 0; ai < 2; ++ai)
; #pragma unroll
;       for (int m = 0; m < 4; ++m) {
;         const int row = u.pm * BM + ai * HALF + wr * 64 + m * 16 + fr;
; #pragma unroll
;         for (int bj = 0; bj < 2; ++bj) {
;           const int c8 = u.pn * BM + bj * HALF + wc * 32 + 8 * fq;
;           const bf16x8 gt = __builtin_nontemporal_load((const bf16x8*)(h + (size_t)row * NPHYS + H_GL + r * 2048 + c8));
;           bf16_t* mp = merged + (size_t)row * DM + c8;
;           f32x4 a0 = acc[ai][bj][m][0], a1 = acc[ai][bj][m][1];
; #pragma unroll
;           for (int j = 0; j < 4; ++j) { a0[j] *= bf2f((bf16_t)gt[j]); a1[j] *= bf2f((bf16_t)gt[4 + j]); }
;           if (r > 0) { const bf16x8 pv = *(const bf16x8*)mp;
; #pragma unroll
;             for (int j = 0; j < 4; ++j) { a0[j] += bf2f((bf16_t)pv[j]); a1[j] += bf2f((bf16_t)pv[4 + j]); } }
;           { u32x4 w = {cvtpk(a0[0], a0[1]), cvtpk(a0[2], a0[3]), cvtpk(a1[0], a1[1]), cvtpk(a1[2], a1[3])}; *(u32x4*)mp = w; }
;         }
;       }
;   }
.LBB0_1700:
	v_cvt_pk_bf16_f32 v54, v54, v55
	v_cvt_pk_bf16_f32 v55, v56, v57
	v_cvt_pk_bf16_f32 v56, v50, v51
	v_add_u32_e32 v50, 0x90, v142
	v_cvt_pk_bf16_f32 v57, v52, v53
	global_store_dwordx4 v[58:59], v[54:57], off offset:256
	v_ashrrev_i32_e32 v51, 31, v50
	v_lshlrev_b64 v[52:53], 12, v[50:51]
	v_mov_b64_e32 v[54:55], s[68:69]
	v_mad_i64_i32 v[50:51], s[22:23], v50, s33, v[54:55]
	v_lshl_add_u64 v[50:51], v[50:51], 0, s[72:73]
	v_lshl_add_u64 v[50:51], v[50:51], 0, v[140:141]
	v_add_co_u32_e32 v54, vcc, s82, v50
	v_lshl_add_u64 v[58:59], s[70:71], 0, v[52:53]
	s_nop 0
	v_addc_co_u32_e32 v55, vcc, 0, v51, vcc
	v_mov_b32_e32 v54, v166
	v_mov_b32_e32 v55, v167
	v_mov_b32_e32 v56, v168
	v_mov_b32_e32 v57, v169
	s_and_b64 vcc, exec, s[2:3]
	v_and_b32_e32 v53, 0xffff0000, v54
	v_lshlrev_b32_e32 v52, 16, v54
	v_pk_mul_f32 v[46:47], v[46:47], v[52:53]
	v_and_b32_e32 v53, 0xffff0000, v56
	v_lshlrev_b32_e32 v52, 16, v56
	v_pk_mul_f32 v[52:53], v[42:43], v[52:53]
	v_and_b32_e32 v43, 0xffff0000, v55
	v_lshlrev_b32_e32 v42, 16, v55
	v_pk_mul_f32 v[48:49], v[48:49], v[42:43]
	v_and_b32_e32 v43, 0xffff0000, v57
	v_lshlrev_b32_e32 v42, 16, v57
	v_pk_mul_f32 v[44:45], v[44:45], v[42:43]
	v_lshl_add_u64 v[42:43], v[58:59], 0, v[140:141]
	s_cbranch_vccnz .LBB0_1702
	v_mov_b32_e32 v54, v198
	v_mov_b32_e32 v55, v199
	v_mov_b32_e32 v56, v200
	v_mov_b32_e32 v57, v201
	v_and_b32_e32 v59, 0xffff0000, v54
	v_lshlrev_b32_e32 v58, 16, v54
	v_pk_add_f32 v[46:47], v[46:47], v[58:59]
	v_and_b32_e32 v59, 0xffff0000, v56
	v_lshlrev_b32_e32 v58, 16, v56
	v_pk_add_f32 v[52:53], v[52:53], v[58:59]
	v_and_b32_e32 v59, 0xffff0000, v55
	v_lshlrev_b32_e32 v58, 16, v55
	v_and_b32_e32 v55, 0xffff0000, v57
	v_lshlrev_b32_e32 v54, 16, v57
	v_pk_add_f32 v[48:49], v[48:49], v[58:59]
	v_pk_add_f32 v[44:45], v[44:45], v[54:55]
.LBB0_1702:
	v_lshl_add_u64 v[50:51], v[50:51], 0, s[76:77]
	v_cvt_pk_bf16_f32 v46, v46, v47
	v_cvt_pk_bf16_f32 v47, v48, v49
	v_cvt_pk_bf16_f32 v48, v52, v53
	v_cvt_pk_bf16_f32 v49, v44, v45
	v_mov_b32_e32 v50, v170
	v_mov_b32_e32 v51, v171
	v_mov_b32_e32 v52, v172
	v_mov_b32_e32 v53, v173
	s_and_b64 vcc, exec, s[2:3]
	global_store_dwordx4 v[42:43], v[46:49], off
	v_and_b32_e32 v45, 0xffff0000, v50
	v_lshlrev_b32_e32 v44, 16, v50
	v_and_b32_e32 v47, 0xffff0000, v52
	v_lshlrev_b32_e32 v46, 16, v52
	v_and_b32_e32 v49, 0xffff0000, v51
	v_lshlrev_b32_e32 v48, 16, v51
	v_and_b32_e32 v51, 0xffff0000, v53
	v_lshlrev_b32_e32 v50, 16, v53
	v_pk_mul_f32 v[38:39], v[38:39], v[44:45]
	v_pk_mul_f32 v[34:35], v[34:35], v[46:47]
	v_pk_mul_f32 v[40:41], v[40:41], v[48:49]
	v_pk_mul_f32 v[36:37], v[36:37], v[50:51]
	s_cbranch_vccnz .LBB0_1704
	v_mov_b32_e32 v44, v202
	v_mov_b32_e32 v45, v203
	v_mov_b32_e32 v46, v204
	v_mov_b32_e32 v47, v205
	v_and_b32_e32 v49, 0xffff0000, v44
	v_lshlrev_b32_e32 v48, 16, v44
	v_pk_add_f32 v[38:39], v[38:39], v[48:49]
	v_and_b32_e32 v49, 0xffff0000, v46
	v_lshlrev_b32_e32 v48, 16, v46
	v_pk_add_f32 v[34:35], v[34:35], v[48:49]
	v_and_b32_e32 v49, 0xffff0000, v45
	v_lshlrev_b32_e32 v48, 16, v45
	v_and_b32_e32 v45, 0xffff0000, v47
	v_lshlrev_b32_e32 v44, 16, v47
	v_pk_add_f32 v[40:41], v[40:41], v[48:49]
	v_pk_add_f32 v[36:37], v[36:37], v[44:45]
.LBB0_1704:
	v_cvt_pk_bf16_f32 v38, v38, v39
	v_cvt_pk_bf16_f32 v39, v40, v41
	v_cvt_pk_bf16_f32 v40, v34, v35
	v_add_u32_e32 v34, 0xa0, v142
	v_cvt_pk_bf16_f32 v41, v36, v37
	global_store_dwordx4 v[42:43], v[38:41], off offset:256
	v_ashrrev_i32_e32 v35, 31, v34
	v_lshlrev_b64 v[36:37], 12, v[34:35]
	v_mov_b64_e32 v[38:39], s[68:69]
	v_mad_i64_i32 v[34:35], s[22:23], v34, s33, v[38:39]
	v_lshl_add_u64 v[34:35], v[34:35], 0, s[72:73]
	v_lshl_add_u64 v[34:35], v[34:35], 0, v[140:141]
	v_add_co_u32_e32 v38, vcc, s82, v34
	v_lshl_add_u64 v[42:43], s[70:71], 0, v[36:37]
	s_nop 0
	v_addc_co_u32_e32 v39, vcc, 0, v35, vcc
	v_mov_b32_e32 v38, v174
	v_mov_b32_e32 v39, v175
	v_mov_b32_e32 v40, v176
	v_mov_b32_e32 v41, v177
	s_and_b64 vcc, exec, s[2:3]
	v_and_b32_e32 v37, 0xffff0000, v38
	v_lshlrev_b32_e32 v36, 16, v38
	v_pk_mul_f32 v[30:31], v[30:31], v[36:37]
	v_and_b32_e32 v37, 0xffff0000, v40
	v_lshlrev_b32_e32 v36, 16, v40
	v_pk_mul_f32 v[36:37], v[26:27], v[36:37]
	v_and_b32_e32 v27, 0xffff0000, v39
	v_lshlrev_b32_e32 v26, 16, v39
	v_pk_mul_f32 v[32:33], v[32:33], v[26:27]
	v_and_b32_e32 v27, 0xffff0000, v41
	v_lshlrev_b32_e32 v26, 16, v41
	v_pk_mul_f32 v[28:29], v[28:29], v[26:27]
	v_lshl_add_u64 v[26:27], v[42:43], 0, v[140:141]
	s_cbranch_vccnz .LBB0_1706
	v_mov_b32_e32 v38, v206
	v_mov_b32_e32 v39, v207
	v_mov_b32_e32 v40, v208
	v_mov_b32_e32 v41, v209
	v_and_b32_e32 v43, 0xffff0000, v38
	v_lshlrev_b32_e32 v42, 16, v38
	v_pk_add_f32 v[30:31], v[30:31], v[42:43]
	v_and_b32_e32 v43, 0xffff0000, v40
	v_lshlrev_b32_e32 v42, 16, v40
	v_pk_add_f32 v[36:37], v[36:37], v[42:43]
	v_and_b32_e32 v43, 0xffff0000, v39
	v_lshlrev_b32_e32 v42, 16, v39
	v_and_b32_e32 v39, 0xffff0000, v41
	v_lshlrev_b32_e32 v38, 16, v41
	v_pk_add_f32 v[32:33], v[32:33], v[42:43]
	v_pk_add_f32 v[28:29], v[28:29], v[38:39]
; DI unsigned cvtpk(float lo, float hi) { unsigned r; asm volatile("v_cvt_pk_bf16_f32 %0, %1, %2" : "=v"(r) : "v"(lo), "v"(hi)); return r; }
; DI float bf2f(bf16_t b) { return __uint_as_float(((unsigned)b) << 16); }
;   DI void operator()(const AccT& acc, const Unit& u, int wr, int wc, int fr, int fq) const {
;     ...
;         const int row = u.pm * BM + ai * HALF + wr * 64 + m * 16 + fr;
; #pragma unroll
;         for (int bj = 0; bj < 2; ++bj) {
;           const int c8 = u.pn * BM + bj * HALF + wc * 32 + 8 * fq;
;           const bf16x8 gt = __builtin_nontemporal_load((const bf16x8*)(h + (size_t)row * NPHYS + H_GL + r * 2048 + c8));
;           bf16_t* mp = merged + (size_t)row * DM + c8;
;           f32x4 a0 = acc[ai][bj][m][0], a1 = acc[ai][bj][m][1];
; #pragma unroll
;           for (int j = 0; j < 4; ++j) { a0[j] *= bf2f((bf16_t)gt[j]); a1[j] *= bf2f((bf16_t)gt[4 + j]); }
;           if (r > 0) { const bf16x8 pv = *(const bf16x8*)mp;
; #pragma unroll
;             for (int j = 0; j < 4; ++j) { a0[j] += bf2f((bf16_t)pv[j]); a1[j] += bf2f((bf16_t)pv[4 + j]); } }
;           { u32x4 w = {cvtpk(a0[0], a0[1]), cvtpk(a0[2], a0[3]), cvtpk(a1[0], a1[1]), cvtpk(a1[2], a1[3])}; *(u32x4*)mp = w; }
;         }
.LBB0_1706:
	v_lshl_add_u64 v[34:35], v[34:35], 0, s[76:77]
	v_cvt_pk_bf16_f32 v30, v30, v31
	v_cvt_pk_bf16_f32 v31, v32, v33
	v_cvt_pk_bf16_f32 v32, v36, v37
	v_cvt_pk_bf16_f32 v33, v28, v29
	v_mov_b32_e32 v34, v178
	v_mov_b32_e32 v35, v179
	v_mov_b32_e32 v36, v180
	v_mov_b32_e32 v37, v181
	s_and_b64 vcc, exec, s[2:3]
	global_store_dwordx4 v[26:27], v[30:33], off
	v_and_b32_e32 v29, 0xffff0000, v34
	v_lshlrev_b32_e32 v28, 16, v34
	v_and_b32_e32 v31, 0xffff0000, v36
	v_lshlrev_b32_e32 v30, 16, v36
	v_and_b32_e32 v33, 0xffff0000, v35
	v_lshlrev_b32_e32 v32, 16, v35
	v_and_b32_e32 v35, 0xffff0000, v37
	v_lshlrev_b32_e32 v34, 16, v37
	v_pk_mul_f32 v[22:23], v[22:23], v[28:29]
	v_pk_mul_f32 v[18:19], v[18:19], v[30:31]
	v_pk_mul_f32 v[24:25], v[24:25], v[32:33]
	v_pk_mul_f32 v[20:21], v[20:21], v[34:35]
	s_cbranch_vccnz .LBB0_1708
	v_mov_b32_e32 v28, v214
	v_mov_b32_e32 v29, v215
	v_mov_b32_e32 v30, v216
	v_mov_b32_e32 v31, v217
	v_and_b32_e32 v33, 0xffff0000, v28
	v_lshlrev_b32_e32 v32, 16, v28
	v_pk_add_f32 v[22:23], v[22:23], v[32:33]
	v_and_b32_e32 v33, 0xffff0000, v30
	v_lshlrev_b32_e32 v32, 16, v30
	v_pk_add_f32 v[18:19], v[18:19], v[32:33]
	v_and_b32_e32 v33, 0xffff0000, v29
	v_lshlrev_b32_e32 v32, 16, v29
	v_and_b32_e32 v29, 0xffff0000, v31
	v_lshlrev_b32_e32 v28, 16, v31
	v_pk_add_f32 v[24:25], v[24:25], v[32:33]
	v_pk_add_f32 v[20:21], v[20:21], v[28:29]
.LBB0_1708:
	v_cvt_pk_bf16_f32 v22, v22, v23
	v_cvt_pk_bf16_f32 v23, v24, v25
	v_cvt_pk_bf16_f32 v24, v18, v19
	v_add_u32_e32 v18, 0xb0, v142
	v_cvt_pk_bf16_f32 v25, v20, v21
	global_store_dwordx4 v[26:27], v[22:25], off offset:256
	v_ashrrev_i32_e32 v19, 31, v18
	v_lshlrev_b64 v[20:21], 12, v[18:19]
	v_mov_b64_e32 v[22:23], s[68:69]
	v_mad_i64_i32 v[18:19], s[22:23], v18, s33, v[22:23]
	v_lshl_add_u64 v[18:19], v[18:19], 0, s[72:73]
	v_lshl_add_u64 v[18:19], v[18:19], 0, v[140:141]
	v_add_co_u32_e32 v22, vcc, s82, v18
	v_lshl_add_u64 v[26:27], s[70:71], 0, v[20:21]
	s_nop 0
	v_addc_co_u32_e32 v23, vcc, 0, v19, vcc
	v_mov_b32_e32 v22, v182
	v_mov_b32_e32 v23, v183
	v_mov_b32_e32 v24, v184
	v_mov_b32_e32 v25, v185
	s_and_b64 vcc, exec, s[2:3]
	v_and_b32_e32 v21, 0xffff0000, v22
	v_lshlrev_b32_e32 v20, 16, v22
	v_pk_mul_f32 v[14:15], v[14:15], v[20:21]
	v_and_b32_e32 v21, 0xffff0000, v24
	v_lshlrev_b32_e32 v20, 16, v24
	v_pk_mul_f32 v[20:21], v[10:11], v[20:21]
	v_and_b32_e32 v11, 0xffff0000, v23
	v_lshlrev_b32_e32 v10, 16, v23
	v_pk_mul_f32 v[16:17], v[16:17], v[10:11]
	v_and_b32_e32 v11, 0xffff0000, v25
	v_lshlrev_b32_e32 v10, 16, v25
	v_pk_mul_f32 v[12:13], v[12:13], v[10:11]
	v_lshl_add_u64 v[10:11], v[26:27], 0, v[140:141]
	s_cbranch_vccnz .LBB0_1710
	v_mov_b32_e32 v22, v224
	v_mov_b32_e32 v23, v225
	v_mov_b32_e32 v24, v226
	v_mov_b32_e32 v25, v227
	v_and_b32_e32 v27, 0xffff0000, v22
	v_lshlrev_b32_e32 v26, 16, v22
	v_pk_add_f32 v[14:15], v[14:15], v[26:27]
	v_and_b32_e32 v27, 0xffff0000, v24
	v_lshlrev_b32_e32 v26, 16, v24
	v_pk_add_f32 v[20:21], v[20:21], v[26:27]
	v_and_b32_e32 v27, 0xffff0000, v23
	v_lshlrev_b32_e32 v26, 16, v23
	v_and_b32_e32 v23, 0xffff0000, v25
	v_lshlrev_b32_e32 v22, 16, v25
	v_pk_add_f32 v[16:17], v[16:17], v[26:27]
	v_pk_add_f32 v[12:13], v[12:13], v[22:23]
.LBB0_1710:
	v_lshl_add_u64 v[18:19], v[18:19], 0, s[76:77]
	v_cvt_pk_bf16_f32 v14, v14, v15
	v_cvt_pk_bf16_f32 v15, v16, v17
	v_cvt_pk_bf16_f32 v16, v20, v21
	v_cvt_pk_bf16_f32 v17, v12, v13
	v_mov_b32_e32 v18, v186
	v_mov_b32_e32 v19, v187
	v_mov_b32_e32 v20, v188
	v_mov_b32_e32 v21, v189
	s_and_b64 vcc, exec, s[2:3]
	global_store_dwordx4 v[10:11], v[14:17], off
	v_and_b32_e32 v13, 0xffff0000, v18
	v_lshlrev_b32_e32 v12, 16, v18
	v_and_b32_e32 v15, 0xffff0000, v20
	v_lshlrev_b32_e32 v14, 16, v20
	v_and_b32_e32 v17, 0xffff0000, v19
	v_lshlrev_b32_e32 v16, 16, v19
	v_and_b32_e32 v19, 0xffff0000, v21
	v_lshlrev_b32_e32 v18, 16, v21
	v_pk_mul_f32 v[6:7], v[6:7], v[12:13]
	v_pk_mul_f32 v[2:3], v[2:3], v[14:15]
	v_pk_mul_f32 v[8:9], v[8:9], v[16:17]
	v_pk_mul_f32 v[4:5], v[4:5], v[18:19]
	s_cbranch_vccnz .LBB0_1712
	v_mov_b32_e32 v12, v232
	v_mov_b32_e32 v13, v233
	v_mov_b32_e32 v14, v234
	v_mov_b32_e32 v15, v235
	v_and_b32_e32 v17, 0xffff0000, v12
	v_lshlrev_b32_e32 v16, 16, v12
	v_pk_add_f32 v[6:7], v[6:7], v[16:17]
	v_and_b32_e32 v17, 0xffff0000, v14
	v_lshlrev_b32_e32 v16, 16, v14
	v_pk_add_f32 v[2:3], v[2:3], v[16:17]
	v_and_b32_e32 v17, 0xffff0000, v13
	v_lshlrev_b32_e32 v16, 16, v13
	v_and_b32_e32 v13, 0xffff0000, v15
	v_lshlrev_b32_e32 v12, 16, v15
	v_pk_add_f32 v[8:9], v[8:9], v[16:17]
	v_pk_add_f32 v[4:5], v[4:5], v[12:13]
